# same as the previous best plus an s_nop 4 between the barrier poll's scalar base update and the load that reads it (robustness, no functional change)
# baseline (speedup 1.0000x reference)
; DI unsigned xb_ld(unsigned* p)              { return __hip_atomic_load(p, __ATOMIC_RELAXED, __HIP_MEMORY_SCOPE_AGENT); }
; DI unsigned xb_add(unsigned* p, unsigned v) { return __hip_atomic_fetch_add(p, v, __ATOMIC_RELAXED, __HIP_MEMORY_SCOPE_AGENT); }
; #define XB_SPIN(cond, bar) do { unsigned _sp = 0; while (cond) { __builtin_amdgcn_s_sleep(1); \
;     if ((++_sp & 255u) == 0u) { if (xb_ld(&(bar)[XB_TMO])) break; if (_sp > XB_SPIN_CAP) { atomicAdd(&(bar)[XB_TMO], 1u); break; } } } } while (0)
; DI void xcd_barrier(const XcdBarrier& b) {
;     ...
;         const unsigned old = xb_add(&bar[XB_XSUB(b.x)], 1u);
;         const unsigned gen = old / nloc;
;         if (old + 1u == (gen + 1u) * nloc) {
;             __builtin_amdgcn_fence(__ATOMIC_RELEASE, "agent");
;             asm volatile("s_waitcnt vmcnt(0)" ::: "memory");
;             const unsigned og = xb_add(&bar[XB_TOP], 1u);
;             const unsigned tg = og / nx;
;             if (og + 1u == (tg + 1u) * nx) xb_add(&bar[XB_TOPGEN], 1u);
;             else XB_SPIN(xb_ld(&bar[XB_TOPGEN]) == tg, bar);
.LBB0_124:
	s_or_b64 exec, exec, s[10:11]
	v_cvt_f32_u32_e32 v4, v2
	s_waitcnt vmcnt(0)
	v_readfirstlane_b32 s0, v3
	v_sub_u32_e32 v3, 0, v2
	v_rcp_iflag_f32_e32 v4, v4
	v_add_u32_e32 v5, s0, v1
	v_mul_f32_e32 v4, 0x4f7ffffe, v4
	v_cvt_u32_f32_e32 v4, v4
	v_mul_lo_u32 v1, v3, v4
	v_mul_hi_u32 v1, v4, v1
	v_add_u32_e32 v1, v4, v1
	v_mul_hi_u32 v1, v5, v1
	v_mul_lo_u32 v3, v1, v2
	v_sub_u32_e32 v3, v5, v3
	v_add_u32_e32 v4, 1, v1
	v_cmp_ge_u32_e32 vcc, v3, v2
	s_nop 1
	v_cndmask_b32_e32 v1, v1, v4, vcc
	v_sub_u32_e32 v4, v3, v2
	v_cndmask_b32_e32 v3, v3, v4, vcc
	v_add_u32_e32 v4, 1, v1
	v_cmp_ge_u32_e32 vcc, v3, v2
	v_add_u32_e32 v3, 1, v5
	s_nop 0
	v_cndmask_b32_e32 v1, v1, v4, vcc
	v_mul_lo_u32 v4, v2, v1
	v_add_u32_e32 v2, v4, v2
	v_cmp_ne_u32_e32 vcc, v3, v2
	s_and_saveexec_b64 s[0:1], vcc
	s_xor_b64 s[8:9], exec, s[0:1]
	s_cbranch_execz .LBB0_138
	s_waitcnt lgkmcnt(0)
	s_add_u32 s16, s70, 0xff20500
	s_addc_u32 s17, s71, 0
	s_nop 4
	v_mov_b32_e32 v0, 0
	global_load_dword v0, v0, s[16:17] sc1
	s_waitcnt vmcnt(0)
	v_cmp_eq_u32_e32 vcc, 0, v0
	s_and_saveexec_b64 s[10:11], vcc
	s_cbranch_execz .LBB0_137
	s_add_u32 s12, s70, 0xff1d200
	s_addc_u32 s13, s71, 0
	s_mov_b32 s0, 1
	s_mov_b64 s[18:19], 0
	v_mov_b32_e32 v0, 0
	s_branch .LBB0_128

; DI unsigned xb_ld(unsigned* p)              { return __hip_atomic_load(p, __ATOMIC_RELAXED, __HIP_MEMORY_SCOPE_AGENT); }
; DI unsigned xb_add(unsigned* p, unsigned v) { return __hip_atomic_fetch_add(p, v, __ATOMIC_RELAXED, __HIP_MEMORY_SCOPE_AGENT); }
; #define XB_SPIN(cond, bar) do { unsigned _sp = 0; while (cond) { __builtin_amdgcn_s_sleep(1); \
;     if ((++_sp & 255u) == 0u) { if (xb_ld(&(bar)[XB_TMO])) break; if (_sp > XB_SPIN_CAP) { atomicAdd(&(bar)[XB_TMO], 1u); break; } } } } while (0)
; DI void xcd_barrier(const XcdBarrier& b) {
;     ...
;         const unsigned old = xb_add(&bar[XB_XSUB(b.x)], 1u);
;         const unsigned gen = old / nloc;
;         if (old + 1u == (gen + 1u) * nloc) {
;             __builtin_amdgcn_fence(__ATOMIC_RELEASE, "agent");
;             asm volatile("s_waitcnt vmcnt(0)" ::: "memory");
;             const unsigned og = xb_add(&bar[XB_TOP], 1u);
;             const unsigned tg = og / nx;
;             if (og + 1u == (tg + 1u) * nx) xb_add(&bar[XB_TOPGEN], 1u);
;             else XB_SPIN(xb_ld(&bar[XB_TOPGEN]) == tg, bar);
.LBB0_1601:
	s_or_b64 exec, exec, s[10:11]
	v_cvt_f32_u32_e32 v4, v2
	s_waitcnt vmcnt(0)
	v_readfirstlane_b32 s0, v3
	v_sub_u32_e32 v3, 0, v2
	v_rcp_iflag_f32_e32 v4, v4
	v_add_u32_e32 v5, s0, v1
	v_mul_f32_e32 v4, 0x4f7ffffe, v4
	v_cvt_u32_f32_e32 v4, v4
	v_mul_lo_u32 v1, v3, v4
	v_mul_hi_u32 v1, v4, v1
	v_add_u32_e32 v1, v4, v1
	v_mul_hi_u32 v1, v5, v1
	v_mul_lo_u32 v3, v1, v2
	v_sub_u32_e32 v3, v5, v3
	v_add_u32_e32 v4, 1, v1
	v_cmp_ge_u32_e32 vcc, v3, v2
	s_nop 1
	v_cndmask_b32_e32 v1, v1, v4, vcc
	v_sub_u32_e32 v4, v3, v2
	v_cndmask_b32_e32 v3, v3, v4, vcc
	v_add_u32_e32 v4, 1, v1
	v_cmp_ge_u32_e32 vcc, v3, v2
	v_add_u32_e32 v3, 1, v5
	s_nop 0
	v_cndmask_b32_e32 v1, v1, v4, vcc
	v_mul_lo_u32 v4, v2, v1
	v_add_u32_e32 v2, v4, v2
	v_cmp_ne_u32_e32 vcc, v3, v2
	s_and_saveexec_b64 s[0:1], vcc
	s_xor_b64 s[8:9], exec, s[0:1]
	s_cbranch_execz .LBB0_1615
	s_waitcnt lgkmcnt(0)
	s_add_u32 s14, s70, 0xff20500
	s_addc_u32 s15, s71, 0
	s_nop 4
	v_mov_b32_e32 v0, 0
	global_load_dword v0, v0, s[14:15] sc1
	s_waitcnt vmcnt(0)
	v_cmp_eq_u32_e32 vcc, 1, v0
	s_and_saveexec_b64 s[10:11], vcc
	s_cbranch_execz .LBB0_1614
	s_add_u32 s12, s70, 0xff1d200
	s_addc_u32 s13, s71, 0
	s_mov_b32 s0, 1
	s_mov_b64 s[16:17], 0
	v_mov_b32_e32 v0, 0
	s_branch .LBB0_1605

; DI unsigned xb_ld(unsigned* p)              { return __hip_atomic_load(p, __ATOMIC_RELAXED, __HIP_MEMORY_SCOPE_AGENT); }
; DI unsigned xb_add(unsigned* p, unsigned v) { return __hip_atomic_fetch_add(p, v, __ATOMIC_RELAXED, __HIP_MEMORY_SCOPE_AGENT); }
; #define XB_SPIN(cond, bar) do { unsigned _sp = 0; while (cond) { __builtin_amdgcn_s_sleep(1); \
;     if ((++_sp & 255u) == 0u) { if (xb_ld(&(bar)[XB_TMO])) break; if (_sp > XB_SPIN_CAP) { atomicAdd(&(bar)[XB_TMO], 1u); break; } } } } while (0)
; DI void xcd_barrier(const XcdBarrier& b) {
;     ...
;         const unsigned old = xb_add(&bar[XB_XSUB(b.x)], 1u);
;         const unsigned gen = old / nloc;
;         if (old + 1u == (gen + 1u) * nloc) {
;             __builtin_amdgcn_fence(__ATOMIC_RELEASE, "agent");
;             asm volatile("s_waitcnt vmcnt(0)" ::: "memory");
;             const unsigned og = xb_add(&bar[XB_TOP], 1u);
;             const unsigned tg = og / nx;
;             if (og + 1u == (tg + 1u) * nx) xb_add(&bar[XB_TOPGEN], 1u);
;             else XB_SPIN(xb_ld(&bar[XB_TOPGEN]) == tg, bar);
.LBB0_1762:
	s_or_b64 exec, exec, s[10:11]
	v_cvt_f32_u32_e32 v4, v2
	s_waitcnt vmcnt(0)
	v_readfirstlane_b32 s0, v3
	v_sub_u32_e32 v3, 0, v2
	v_rcp_iflag_f32_e32 v4, v4
	v_add_u32_e32 v5, s0, v1
	v_mul_f32_e32 v4, 0x4f7ffffe, v4
	v_cvt_u32_f32_e32 v4, v4
	v_mul_lo_u32 v1, v3, v4
	v_mul_hi_u32 v1, v4, v1
	v_add_u32_e32 v1, v4, v1
	v_mul_hi_u32 v1, v5, v1
	v_mul_lo_u32 v3, v1, v2
	v_sub_u32_e32 v3, v5, v3
	v_add_u32_e32 v4, 1, v1
	v_cmp_ge_u32_e32 vcc, v3, v2
	s_nop 1
	v_cndmask_b32_e32 v1, v1, v4, vcc
	v_sub_u32_e32 v4, v3, v2
	v_cndmask_b32_e32 v3, v3, v4, vcc
	v_add_u32_e32 v4, 1, v1
	v_cmp_ge_u32_e32 vcc, v3, v2
	v_add_u32_e32 v3, 1, v5
	s_nop 0
	v_cndmask_b32_e32 v1, v1, v4, vcc
	v_mul_lo_u32 v4, v2, v1
	v_add_u32_e32 v2, v4, v2
	v_cmp_ne_u32_e32 vcc, v3, v2
	s_and_saveexec_b64 s[0:1], vcc
	s_xor_b64 s[8:9], exec, s[0:1]
	s_cbranch_execz .LBB0_1776
	s_waitcnt lgkmcnt(0)
	s_add_u32 s14, s70, 0xff20500
	s_addc_u32 s15, s71, 0
	s_nop 4
	v_mov_b32_e32 v0, 0
	global_load_dword v0, v0, s[14:15] sc1
	s_waitcnt vmcnt(0)
	v_cmp_eq_u32_e32 vcc, 2, v0
	s_and_saveexec_b64 s[10:11], vcc
	s_cbranch_execz .LBB0_1775
	s_add_u32 s12, s70, 0xff1d200
	s_addc_u32 s13, s71, 0
	s_mov_b32 s0, 1
	s_mov_b64 s[16:17], 0
	v_mov_b32_e32 v0, 0
	s_branch .LBB0_1766

; DI unsigned xb_ld(unsigned* p)              { return __hip_atomic_load(p, __ATOMIC_RELAXED, __HIP_MEMORY_SCOPE_AGENT); }
; DI unsigned xb_add(unsigned* p, unsigned v) { return __hip_atomic_fetch_add(p, v, __ATOMIC_RELAXED, __HIP_MEMORY_SCOPE_AGENT); }
; #define XB_SPIN(cond, bar) do { unsigned _sp = 0; while (cond) { __builtin_amdgcn_s_sleep(1); \
;     if ((++_sp & 255u) == 0u) { if (xb_ld(&(bar)[XB_TMO])) break; if (_sp > XB_SPIN_CAP) { atomicAdd(&(bar)[XB_TMO], 1u); break; } } } } while (0)
; DI void xcd_barrier(const XcdBarrier& b) {
;     ...
;         const unsigned old = xb_add(&bar[XB_XSUB(b.x)], 1u);
;         const unsigned gen = old / nloc;
;         if (old + 1u == (gen + 1u) * nloc) {
;             __builtin_amdgcn_fence(__ATOMIC_RELEASE, "agent");
;             asm volatile("s_waitcnt vmcnt(0)" ::: "memory");
;             const unsigned og = xb_add(&bar[XB_TOP], 1u);
;             const unsigned tg = og / nx;
;             if (og + 1u == (tg + 1u) * nx) xb_add(&bar[XB_TOPGEN], 1u);
;             else XB_SPIN(xb_ld(&bar[XB_TOPGEN]) == tg, bar);
.LBB0_1873:
	s_or_b64 exec, exec, s[10:11]
	v_cvt_f32_u32_e32 v4, v2
	s_waitcnt vmcnt(0)
	v_readfirstlane_b32 s0, v3
	v_sub_u32_e32 v3, 0, v2
	v_rcp_iflag_f32_e32 v4, v4
	v_add_u32_e32 v5, s0, v1
	v_mul_f32_e32 v4, 0x4f7ffffe, v4
	v_cvt_u32_f32_e32 v4, v4
	v_mul_lo_u32 v1, v3, v4
	v_mul_hi_u32 v1, v4, v1
	v_add_u32_e32 v1, v4, v1
	v_mul_hi_u32 v1, v5, v1
	v_mul_lo_u32 v3, v1, v2
	v_sub_u32_e32 v3, v5, v3
	v_add_u32_e32 v4, 1, v1
	v_cmp_ge_u32_e32 vcc, v3, v2
	s_nop 1
	v_cndmask_b32_e32 v1, v1, v4, vcc
	v_sub_u32_e32 v4, v3, v2
	v_cndmask_b32_e32 v3, v3, v4, vcc
	v_add_u32_e32 v4, 1, v1
	v_cmp_ge_u32_e32 vcc, v3, v2
	v_add_u32_e32 v3, 1, v5
	s_nop 0
	v_cndmask_b32_e32 v1, v1, v4, vcc
	v_mul_lo_u32 v4, v2, v1
	v_add_u32_e32 v2, v4, v2
	v_cmp_ne_u32_e32 vcc, v3, v2
	s_and_saveexec_b64 s[8:9], vcc
	s_xor_b64 s[8:9], exec, s[8:9]
	s_cbranch_execz .LBB0_1887
	s_waitcnt lgkmcnt(0)
	s_add_u32 s14, s70, 0xff20500
	s_addc_u32 s15, s71, 0
	s_nop 4
	v_mov_b32_e32 v0, 0
	global_load_dword v0, v0, s[14:15] sc1
	s_waitcnt vmcnt(0)
	v_cmp_eq_u32_e32 vcc, 3, v0
	s_and_saveexec_b64 s[10:11], vcc
	s_cbranch_execz .LBB0_1886
	s_add_u32 s12, s70, 0xff1d200
	s_addc_u32 s13, s71, 0
	s_mov_b32 s0, 1
	s_mov_b64 s[16:17], 0
	v_mov_b32_e32 v0, 0
	s_branch .LBB0_1877

; DI unsigned xb_ld(unsigned* p)              { return __hip_atomic_load(p, __ATOMIC_RELAXED, __HIP_MEMORY_SCOPE_AGENT); }
; DI unsigned xb_add(unsigned* p, unsigned v) { return __hip_atomic_fetch_add(p, v, __ATOMIC_RELAXED, __HIP_MEMORY_SCOPE_AGENT); }
; #define XB_SPIN(cond, bar) do { unsigned _sp = 0; while (cond) { __builtin_amdgcn_s_sleep(1); \
;     if ((++_sp & 255u) == 0u) { if (xb_ld(&(bar)[XB_TMO])) break; if (_sp > XB_SPIN_CAP) { atomicAdd(&(bar)[XB_TMO], 1u); break; } } } } while (0)
; DI void xcd_barrier(const XcdBarrier& b) {
;     ...
;         const unsigned old = xb_add(&bar[XB_XSUB(b.x)], 1u);
;         const unsigned gen = old / nloc;
;         if (old + 1u == (gen + 1u) * nloc) {
;             __builtin_amdgcn_fence(__ATOMIC_RELEASE, "agent");
;             asm volatile("s_waitcnt vmcnt(0)" ::: "memory");
;             const unsigned og = xb_add(&bar[XB_TOP], 1u);
;             const unsigned tg = og / nx;
;             if (og + 1u == (tg + 1u) * nx) xb_add(&bar[XB_TOPGEN], 1u);
;             else XB_SPIN(xb_ld(&bar[XB_TOPGEN]) == tg, bar);
.LBB0_1957:
	s_or_b64 exec, exec, s[16:17]
	v_cvt_f32_u32_e32 v4, v2
	s_waitcnt vmcnt(0)
	v_readfirstlane_b32 s0, v3
	v_sub_u32_e32 v3, 0, v2
	v_rcp_iflag_f32_e32 v4, v4
	v_add_u32_e32 v5, s0, v1
	v_mul_f32_e32 v4, 0x4f7ffffe, v4
	v_cvt_u32_f32_e32 v4, v4
	v_mul_lo_u32 v1, v3, v4
	v_mul_hi_u32 v1, v4, v1
	v_add_u32_e32 v1, v4, v1
	v_mul_hi_u32 v1, v5, v1
	v_mul_lo_u32 v3, v1, v2
	v_sub_u32_e32 v3, v5, v3
	v_add_u32_e32 v4, 1, v1
	v_cmp_ge_u32_e32 vcc, v3, v2
	s_nop 1
	v_cndmask_b32_e32 v1, v1, v4, vcc
	v_sub_u32_e32 v4, v3, v2
	v_cndmask_b32_e32 v3, v3, v4, vcc
	v_add_u32_e32 v4, 1, v1
	v_cmp_ge_u32_e32 vcc, v3, v2
	v_add_u32_e32 v3, 1, v5
	s_nop 0
	v_cndmask_b32_e32 v1, v1, v4, vcc
	v_mul_lo_u32 v4, v2, v1
	v_add_u32_e32 v2, v4, v2
	v_cmp_ne_u32_e32 vcc, v3, v2
	s_and_saveexec_b64 s[0:1], vcc
	s_xor_b64 s[14:15], exec, s[0:1]
	s_cbranch_execz .LBB0_1971
	s_waitcnt lgkmcnt(0)
	s_add_u32 s20, s70, 0xff20500
	s_addc_u32 s21, s71, 0
	s_nop 4
	v_mov_b32_e32 v0, 0
	global_load_dword v0, v0, s[20:21] sc1
	s_waitcnt vmcnt(0)
	v_cmp_eq_u32_e32 vcc, 4, v0
	s_and_saveexec_b64 s[16:17], vcc
	s_cbranch_execz .LBB0_1970
	s_add_u32 s18, s70, 0xff1d200
	s_addc_u32 s19, s71, 0
	s_mov_b32 s0, 1
	s_mov_b64 s[22:23], 0
	v_mov_b32_e32 v0, 0
	s_branch .LBB0_1961
